# group-barrier fast path: buffer_inv sc1 issued right after the arrive atomic so it completes under the poll (workgroup is parked, polls bypass L1); on top of v44
# speedup vs baseline: 1.0292x; 1.0292x over previous
; __device__ __forceinline__ unsigned xb_ld(unsigned* p)              { return __hip_atomic_load(p, __ATOMIC_RELAXED, __HIP_MEMORY_SCOPE_AGENT); }
; __device__ __forceinline__ unsigned xb_add(unsigned* p, unsigned v) { return __hip_atomic_fetch_add(p, v, __ATOMIC_RELAXED, __HIP_MEMORY_SCOPE_AGENT); }
; #define XB_SPIN(cond, bar) do { unsigned _sp = 0; while (cond) { __builtin_amdgcn_s_sleep(1); \
;     if ((++_sp & 255u) == 0u) { if (xb_ld(&(bar)[XB_TMO])) break; if (_sp > XB_SPIN_CAP) { atomicAdd(&(bar)[XB_TMO], 1u); break; } } } } while (0)
; __device__ __forceinline__ void xcd_barrier(const XcdBarrier& b) {
;     asm volatile("s_waitcnt vmcnt(0)" ::: "memory");
;     __syncthreads();
;     if (threadIdx.x == 0) {
;         unsigned* bar = b.bar;
;         __builtin_amdgcn_s_waitcnt(0);
;         unsigned nloc = b.st[0], nx = b.st[1];
;         if (nloc == 0u) { xcd_barrier_complete(bar, b.x, nloc, nx); b.st[0] = nloc; b.st[1] = nx; }
;         const unsigned old = xb_add(&bar[XB_XSUB(b.x)], 1u);
;         const unsigned gen = old / nloc;
;         if (old + 1u == (gen + 1u) * nloc) {
;             __builtin_amdgcn_fence(__ATOMIC_RELEASE, "agent");
;             asm volatile("s_waitcnt vmcnt(0)" ::: "memory");
;             const unsigned og = xb_add(&bar[XB_TOP], 1u);
;             const unsigned tg = og / nx;
;             if (og + 1u == (tg + 1u) * nx) xb_add(&bar[XB_TOPGEN], 1u);
;             else XB_SPIN(xb_ld(&bar[XB_TOPGEN]) == tg, bar);
;             __builtin_amdgcn_fence(__ATOMIC_ACQUIRE, "agent");
;             xb_add(&bar[XB_XGEN(b.x)], 1u);
;             asm volatile("s_waitcnt vmcnt(0)" ::: "memory");
;         } else {
;             XB_SPIN(xb_ld(&bar[XB_XGEN(b.x)]) == gen, bar);
;             __builtin_amdgcn_fence(__ATOMIC_ACQUIRE, "agent");
;             asm volatile("s_waitcnt vmcnt(0)" ::: "memory");
;         }
;     }
;     __syncthreads();
.Lgb_have_flag:
	s_cmp_eq_u32 s40, 1
	s_cbranch_scc0 .Lgb_orig_g1
	s_and_b32 s40, s2, 7
	s_lshl_b32 s40, s40, 7
	s_add_u32 s38, s24, 0x313800
	s_addc_u32 s39, s25, 0
	v_mov_b32_e32 v0, s40
	v_mov_b32_e32 v1, 1
	global_atomic_add v2, v0, v1, s[38:39] sc0
	s_mov_b32 s40, 0
	s_waitcnt vmcnt(0)
	buffer_inv sc1
	v_or_b32_e32 v2, 31, v2
	v_add_u32_e32 v2, 1, v2
.Lgb_spin_g1:
	global_load_dword v3, v0, s[38:39] sc1
	s_waitcnt vmcnt(0)
	v_sub_u32_e32 v3, v3, v2
	v_cmp_gt_i32_e32 vcc, 0, v3
	s_cbranch_vccz .Lgb_done_g1
	s_sleep 1
	s_add_i32 s40, s40, 1
	s_cmp_lt_u32 s40, 0x100000
	s_cbranch_scc1 .Lgb_spin_g1
.Lgb_done_g1:
	s_branch .LBB0_1165
.Lgb_orig_g1:
	v_readlane_b32 s8, v254, 56
	s_waitcnt vmcnt(0) expcnt(0) lgkmcnt(0)
	s_nop 0
	v_mov_b32_e32 v0, s8
	ds_read_b32 v2, v0
	v_readlane_b32 s8, v254, 57
	s_waitcnt lgkmcnt(0)
	v_cmp_ne_u32_e32 vcc, 0, v2
	v_mov_b32_e32 v0, s8
	ds_read_b32 v0, v0
	s_cbranch_vccnz .LBB0_1129
	s_mov_b32 s8, 1
	s_branch .LBB0_1117

; __device__ __forceinline__ unsigned xb_ld(unsigned* p)              { return __hip_atomic_load(p, __ATOMIC_RELAXED, __HIP_MEMORY_SCOPE_AGENT); }
; __device__ __forceinline__ unsigned xb_add(unsigned* p, unsigned v) { return __hip_atomic_fetch_add(p, v, __ATOMIC_RELAXED, __HIP_MEMORY_SCOPE_AGENT); }
; #define XB_SPIN(cond, bar) do { unsigned _sp = 0; while (cond) { __builtin_amdgcn_s_sleep(1); \
;     if ((++_sp & 255u) == 0u) { if (xb_ld(&(bar)[XB_TMO])) break; if (_sp > XB_SPIN_CAP) { atomicAdd(&(bar)[XB_TMO], 1u); break; } } } } while (0)
; __device__ __forceinline__ void xcd_barrier(const XcdBarrier& b) {
;     asm volatile("s_waitcnt vmcnt(0)" ::: "memory");
;     __syncthreads();
;     if (threadIdx.x == 0) {
;         unsigned* bar = b.bar;
;         __builtin_amdgcn_s_waitcnt(0);
;         unsigned nloc = b.st[0], nx = b.st[1];
;         if (nloc == 0u) { xcd_barrier_complete(bar, b.x, nloc, nx); b.st[0] = nloc; b.st[1] = nx; }
;         const unsigned old = xb_add(&bar[XB_XSUB(b.x)], 1u);
;         const unsigned gen = old / nloc;
;         if (old + 1u == (gen + 1u) * nloc) {
;             __builtin_amdgcn_fence(__ATOMIC_RELEASE, "agent");
;             asm volatile("s_waitcnt vmcnt(0)" ::: "memory");
;             const unsigned og = xb_add(&bar[XB_TOP], 1u);
;             const unsigned tg = og / nx;
;             if (og + 1u == (tg + 1u) * nx) xb_add(&bar[XB_TOPGEN], 1u);
;             else XB_SPIN(xb_ld(&bar[XB_TOPGEN]) == tg, bar);
;             __builtin_amdgcn_fence(__ATOMIC_ACQUIRE, "agent");
;             xb_add(&bar[XB_XGEN(b.x)], 1u);
;             asm volatile("s_waitcnt vmcnt(0)" ::: "memory");
;         } else {
;             XB_SPIN(xb_ld(&bar[XB_XGEN(b.x)]) == gen, bar);
;             __builtin_amdgcn_fence(__ATOMIC_ACQUIRE, "agent");
;             asm volatile("s_waitcnt vmcnt(0)" ::: "memory");
;         }
;     }
;     __syncthreads();
.LBB0_1245:
	s_add_i32 s0, s86, 1
	s_cmp_ge_i32 s0, s27
	s_cbranch_scc1 .LBB0_1299
	s_waitcnt vmcnt(0)
	s_waitcnt lgkmcnt(0)
	s_barrier
	s_mov_b64 s[0:1], exec
	v_readlane_b32 s8, v252, 32
	v_readlane_b32 s9, v252, 33
	v_readlane_b32 s44, v252, 46
	s_and_b64 s[8:9], s[0:1], s[8:9]
	v_readlane_b32 s45, v252, 47
	s_mov_b64 exec, s[8:9]
	s_cbranch_execz .LBB0_1298
	v_mov_b32_e32 v0, 0x23fc8
	ds_read_b32 v1, v0
	s_waitcnt lgkmcnt(0)
	v_readfirstlane_b32 s40, v1
	s_cmp_eq_u32 s40, 1
	s_cbranch_scc0 .Lgb_orig_pool
	s_and_b32 s40, s2, 7
	s_lshl_b32 s40, s40, 7
	s_add_u32 s38, s24, 0x313800
	s_addc_u32 s39, s25, 0
	v_mov_b32_e32 v0, s40
	v_mov_b32_e32 v1, 1
	global_atomic_add v2, v0, v1, s[38:39] sc0
	s_mov_b32 s40, 0
	s_waitcnt vmcnt(0)
	buffer_inv sc1
	v_or_b32_e32 v2, 31, v2
	v_add_u32_e32 v2, 1, v2
.Lgb_spin_pool:
	global_load_dword v3, v0, s[38:39] sc1
	s_waitcnt vmcnt(0)
	v_sub_u32_e32 v3, v3, v2
	v_cmp_gt_i32_e32 vcc, 0, v3
	s_cbranch_vccz .Lgb_done_pool
	s_sleep 1
	s_add_i32 s40, s40, 1
	s_cmp_lt_u32 s40, 0x100000
	s_cbranch_scc1 .Lgb_spin_pool
.Lgb_done_pool:
	s_branch .LBB0_1298
.Lgb_orig_pool:
	v_readlane_b32 s8, v254, 56
	s_waitcnt vmcnt(0) expcnt(0) lgkmcnt(0)
	s_nop 0
	v_mov_b32_e32 v0, s8
	ds_read_b32 v2, v0
	v_readlane_b32 s8, v254, 57
	s_waitcnt lgkmcnt(0)
	v_cmp_ne_u32_e32 vcc, 0, v2
	v_mov_b32_e32 v0, s8
	ds_read_b32 v0, v0
	s_cbranch_vccnz .LBB0_1262
	s_mov_b32 s8, 1
	s_branch .LBB0_1250

; __device__ __forceinline__ unsigned xb_ld(unsigned* p)              { return __hip_atomic_load(p, __ATOMIC_RELAXED, __HIP_MEMORY_SCOPE_AGENT); }
; __device__ __forceinline__ unsigned xb_add(unsigned* p, unsigned v) { return __hip_atomic_fetch_add(p, v, __ATOMIC_RELAXED, __HIP_MEMORY_SCOPE_AGENT); }
; #define XB_SPIN(cond, bar) do { unsigned _sp = 0; while (cond) { __builtin_amdgcn_s_sleep(1); \
;     if ((++_sp & 255u) == 0u) { if (xb_ld(&(bar)[XB_TMO])) break; if (_sp > XB_SPIN_CAP) { atomicAdd(&(bar)[XB_TMO], 1u); break; } } } } while (0)
; __device__ __forceinline__ void xcd_barrier(const XcdBarrier& b) {
;     asm volatile("s_waitcnt vmcnt(0)" ::: "memory");
;     __syncthreads();
;     if (threadIdx.x == 0) {
;         unsigned* bar = b.bar;
;         __builtin_amdgcn_s_waitcnt(0);
;         unsigned nloc = b.st[0], nx = b.st[1];
;         if (nloc == 0u) { xcd_barrier_complete(bar, b.x, nloc, nx); b.st[0] = nloc; b.st[1] = nx; }
;         const unsigned old = xb_add(&bar[XB_XSUB(b.x)], 1u);
;         const unsigned gen = old / nloc;
;         if (old + 1u == (gen + 1u) * nloc) {
;             __builtin_amdgcn_fence(__ATOMIC_RELEASE, "agent");
;             asm volatile("s_waitcnt vmcnt(0)" ::: "memory");
;             const unsigned og = xb_add(&bar[XB_TOP], 1u);
;             const unsigned tg = og / nx;
;             if (og + 1u == (tg + 1u) * nx) xb_add(&bar[XB_TOPGEN], 1u);
;             else XB_SPIN(xb_ld(&bar[XB_TOPGEN]) == tg, bar);
;             __builtin_amdgcn_fence(__ATOMIC_ACQUIRE, "agent");
;             xb_add(&bar[XB_XGEN(b.x)], 1u);
;             asm volatile("s_waitcnt vmcnt(0)" ::: "memory");
;         } else {
;             XB_SPIN(xb_ld(&bar[XB_XGEN(b.x)]) == gen, bar);
;             __builtin_amdgcn_fence(__ATOMIC_ACQUIRE, "agent");
;             asm volatile("s_waitcnt vmcnt(0)" ::: "memory");
;         }
;     }
;     __syncthreads();
.LBB0_1377:
	s_add_i32 s66, s86, 2
	s_cmp_ge_i32 s66, s27
	s_cbranch_scc1 .LBB0_1389
	s_waitcnt vmcnt(0)
	s_waitcnt lgkmcnt(0)
	s_barrier
	s_mov_b64 s[0:1], exec
	v_readlane_b32 s38, v252, 32
	v_readlane_b32 s39, v252, 33
	v_readlane_b32 s46, v252, 46
	s_and_b64 s[38:39], s[0:1], s[38:39]
	v_readlane_b32 s47, v252, 47
	s_mov_b64 exec, s[38:39]
	s_cbranch_execz .LBB0_1617
	v_mov_b32_e32 v0, 0x23fc8
	ds_read_b32 v1, v0
	s_waitcnt lgkmcnt(0)
	v_readfirstlane_b32 s40, v1
	s_cmp_eq_u32 s40, 1
	s_cbranch_scc0 .Lgb_orig_attn
	s_and_b32 s40, s2, 7
	s_lshl_b32 s40, s40, 7
	s_add_u32 s38, s24, 0x313800
	s_addc_u32 s39, s25, 0
	v_mov_b32_e32 v0, s40
	v_mov_b32_e32 v1, 1
	global_atomic_add v2, v0, v1, s[38:39] sc0
	s_mov_b32 s40, 0
	s_waitcnt vmcnt(0)
	buffer_inv sc1
	v_or_b32_e32 v2, 31, v2
	v_add_u32_e32 v2, 1, v2
.Lgb_spin_attn:
	global_load_dword v3, v0, s[38:39] sc1
	s_waitcnt vmcnt(0)
	v_sub_u32_e32 v3, v3, v2
	v_cmp_gt_i32_e32 vcc, 0, v3
	s_cbranch_vccz .Lgb_done_attn
	s_sleep 1
	s_add_i32 s40, s40, 1
	s_cmp_lt_u32 s40, 0x100000
	s_cbranch_scc1 .Lgb_spin_attn
.Lgb_done_attn:
	s_branch .LBB0_1617
.Lgb_orig_attn:
	v_readlane_b32 s9, v254, 56
	s_waitcnt vmcnt(0) expcnt(0) lgkmcnt(0)
	s_nop 0
	v_mov_b32_e32 v0, s9
	ds_read_b32 v2, v0
	v_readlane_b32 s9, v254, 57
	s_waitcnt lgkmcnt(0)
	v_cmp_ne_u32_e32 vcc, 0, v2
	v_mov_b32_e32 v0, s9
	ds_read_b32 v0, v0
	s_cbranch_vccnz .LBB0_1573
	s_mov_b32 s9, 1
	s_branch .LBB0_1382

; __device__ __forceinline__ unsigned xb_ld(unsigned* p)              { return __hip_atomic_load(p, __ATOMIC_RELAXED, __HIP_MEMORY_SCOPE_AGENT); }
; __device__ __forceinline__ unsigned xb_add(unsigned* p, unsigned v) { return __hip_atomic_fetch_add(p, v, __ATOMIC_RELAXED, __HIP_MEMORY_SCOPE_AGENT); }
; #define XB_SPIN(cond, bar) do { unsigned _sp = 0; while (cond) { __builtin_amdgcn_s_sleep(1); \
;     if ((++_sp & 255u) == 0u) { if (xb_ld(&(bar)[XB_TMO])) break; if (_sp > XB_SPIN_CAP) { atomicAdd(&(bar)[XB_TMO], 1u); break; } } } } while (0)
; __device__ __forceinline__ void xcd_barrier(const XcdBarrier& b) {
;     asm volatile("s_waitcnt vmcnt(0)" ::: "memory");
;     __syncthreads();
;     if (threadIdx.x == 0) {
;         unsigned* bar = b.bar;
;         __builtin_amdgcn_s_waitcnt(0);
;         unsigned nloc = b.st[0], nx = b.st[1];
;         if (nloc == 0u) { xcd_barrier_complete(bar, b.x, nloc, nx); b.st[0] = nloc; b.st[1] = nx; }
;         const unsigned old = xb_add(&bar[XB_XSUB(b.x)], 1u);
;         const unsigned gen = old / nloc;
;         if (old + 1u == (gen + 1u) * nloc) {
;             __builtin_amdgcn_fence(__ATOMIC_RELEASE, "agent");
;             asm volatile("s_waitcnt vmcnt(0)" ::: "memory");
;             const unsigned og = xb_add(&bar[XB_TOP], 1u);
;             const unsigned tg = og / nx;
;             if (og + 1u == (tg + 1u) * nx) xb_add(&bar[XB_TOPGEN], 1u);
;             else XB_SPIN(xb_ld(&bar[XB_TOPGEN]) == tg, bar);
;             __builtin_amdgcn_fence(__ATOMIC_ACQUIRE, "agent");
;             xb_add(&bar[XB_XGEN(b.x)], 1u);
;             asm volatile("s_waitcnt vmcnt(0)" ::: "memory");
;         } else {
;             XB_SPIN(xb_ld(&bar[XB_XGEN(b.x)]) == gen, bar);
;             __builtin_amdgcn_fence(__ATOMIC_ACQUIRE, "agent");
;             asm volatile("s_waitcnt vmcnt(0)" ::: "memory");
;         }
;     }
;     __syncthreads();
.LBB0_1672:
	s_add_i32 s8, s66, 1
	s_cmp_ge_i32 s8, s27
	s_cbranch_scc1 .LBB0_1684
	s_waitcnt vmcnt(0)
	s_waitcnt lgkmcnt(0)
	s_barrier
	s_mov_b64 s[0:1], exec
	v_readlane_b32 s38, v252, 32
	v_readlane_b32 s39, v252, 33
	v_readlane_b32 s46, v252, 46
	s_and_b64 s[38:39], s[0:1], s[38:39]
	v_readlane_b32 s47, v252, 47
	s_mov_b64 exec, s[38:39]
	s_cbranch_execz .LBB0_1727
	v_mov_b32_e32 v0, 0x23fc8
	ds_read_b32 v1, v0
	s_waitcnt lgkmcnt(0)
	v_readfirstlane_b32 s40, v1
	s_cmp_eq_u32 s40, 1
	s_cbranch_scc0 .Lgb_orig_g2
	s_and_b32 s40, s2, 7
	s_lshl_b32 s40, s40, 7
	s_add_u32 s38, s24, 0x313800
	s_addc_u32 s39, s25, 0
	v_mov_b32_e32 v0, s40
	v_mov_b32_e32 v1, 1
	global_atomic_add v2, v0, v1, s[38:39] sc0
	s_mov_b32 s40, 0
	s_waitcnt vmcnt(0)
	buffer_inv sc1
	v_or_b32_e32 v2, 31, v2
	v_add_u32_e32 v2, 1, v2
.Lgb_spin_g2:
	global_load_dword v3, v0, s[38:39] sc1
	s_waitcnt vmcnt(0)
	v_sub_u32_e32 v3, v3, v2
	v_cmp_gt_i32_e32 vcc, 0, v3
	s_cbranch_vccz .Lgb_done_g2
	s_sleep 1
	s_add_i32 s40, s40, 1
	s_cmp_lt_u32 s40, 0x100000
	s_cbranch_scc1 .Lgb_spin_g2
.Lgb_done_g2:
	s_branch .LBB0_1727
.Lgb_orig_g2:
	v_readlane_b32 s9, v254, 56
	s_waitcnt vmcnt(0) expcnt(0) lgkmcnt(0)
	s_nop 0
	v_mov_b32_e32 v0, s9
	ds_read_b32 v2, v0
	v_readlane_b32 s9, v254, 57
	s_waitcnt lgkmcnt(0)
	v_cmp_ne_u32_e32 vcc, 0, v2
	v_mov_b32_e32 v0, s9
	ds_read_b32 v0, v0
	s_cbranch_vccnz .LBB0_1691
	s_mov_b32 s9, 1
	s_branch .LBB0_1677

; __device__ __forceinline__ unsigned xb_ld(unsigned* p)              { return __hip_atomic_load(p, __ATOMIC_RELAXED, __HIP_MEMORY_SCOPE_AGENT); }
; __device__ __forceinline__ unsigned xb_add(unsigned* p, unsigned v) { return __hip_atomic_fetch_add(p, v, __ATOMIC_RELAXED, __HIP_MEMORY_SCOPE_AGENT); }
; #define XB_SPIN(cond, bar) do { unsigned _sp = 0; while (cond) { __builtin_amdgcn_s_sleep(1); \
;     if ((++_sp & 255u) == 0u) { if (xb_ld(&(bar)[XB_TMO])) break; if (_sp > XB_SPIN_CAP) { atomicAdd(&(bar)[XB_TMO], 1u); break; } } } } while (0)
; __device__ __forceinline__ void xcd_barrier(const XcdBarrier& b) {
;     asm volatile("s_waitcnt vmcnt(0)" ::: "memory");
;     __syncthreads();
;     if (threadIdx.x == 0) {
;         unsigned* bar = b.bar;
;         __builtin_amdgcn_s_waitcnt(0);
;         unsigned nloc = b.st[0], nx = b.st[1];
;         if (nloc == 0u) { xcd_barrier_complete(bar, b.x, nloc, nx); b.st[0] = nloc; b.st[1] = nx; }
;         const unsigned old = xb_add(&bar[XB_XSUB(b.x)], 1u);
;         const unsigned gen = old / nloc;
;         if (old + 1u == (gen + 1u) * nloc) {
;             __builtin_amdgcn_fence(__ATOMIC_RELEASE, "agent");
;             asm volatile("s_waitcnt vmcnt(0)" ::: "memory");
;             const unsigned og = xb_add(&bar[XB_TOP], 1u);
;             const unsigned tg = og / nx;
;             if (og + 1u == (tg + 1u) * nx) xb_add(&bar[XB_TOPGEN], 1u);
;             else XB_SPIN(xb_ld(&bar[XB_TOPGEN]) == tg, bar);
;             __builtin_amdgcn_fence(__ATOMIC_ACQUIRE, "agent");
;             xb_add(&bar[XB_XGEN(b.x)], 1u);
;             asm volatile("s_waitcnt vmcnt(0)" ::: "memory");
;         } else {
;             XB_SPIN(xb_ld(&bar[XB_XGEN(b.x)]) == gen, bar);
;             __builtin_amdgcn_fence(__ATOMIC_ACQUIRE, "agent");
;             asm volatile("s_waitcnt vmcnt(0)" ::: "memory");
;         }
;     }
;     __syncthreads();
.LBB0_1775:
	s_add_i32 s8, s66, 2
	s_cmp_ge_i32 s8, s27
	s_cbranch_scc1 .LBB0_1829
	s_waitcnt vmcnt(0)
	s_waitcnt vmcnt(0) lgkmcnt(0)
	s_barrier
	s_mov_b64 s[0:1], exec
	v_readlane_b32 s38, v252, 32
	v_readlane_b32 s39, v252, 33
	s_and_b64 s[38:39], s[0:1], s[38:39]
	s_mov_b64 exec, s[38:39]
	s_cbranch_execz .LBB0_1828
	v_mov_b32_e32 v0, 0x23fc8
	ds_read_b32 v1, v0
	s_waitcnt lgkmcnt(0)
	v_readfirstlane_b32 s40, v1
	s_cmp_eq_u32 s40, 1
	s_cbranch_scc0 .Lgb_orig_g3
	s_and_b32 s40, s2, 7
	s_lshl_b32 s40, s40, 7
	s_add_u32 s38, s24, 0x313800
	s_addc_u32 s39, s25, 0
	v_mov_b32_e32 v0, s40
	v_mov_b32_e32 v1, 1
	global_atomic_add v2, v0, v1, s[38:39] sc0
	s_mov_b32 s40, 0
	s_waitcnt vmcnt(0)
	buffer_inv sc1
	v_or_b32_e32 v2, 31, v2
	v_add_u32_e32 v2, 1, v2
.Lgb_spin_g3:
	global_load_dword v3, v0, s[38:39] sc1
	s_waitcnt vmcnt(0)
	v_sub_u32_e32 v3, v3, v2
	v_cmp_gt_i32_e32 vcc, 0, v3
	s_cbranch_vccz .Lgb_done_g3
	s_sleep 1
	s_add_i32 s40, s40, 1
	s_cmp_lt_u32 s40, 0x100000
	s_cbranch_scc1 .Lgb_spin_g3
.Lgb_done_g3:
	s_branch .LBB0_1828
.Lgb_orig_g3:
	v_readlane_b32 s9, v254, 56
	s_waitcnt vmcnt(0) expcnt(0) lgkmcnt(0)
	s_nop 0
	v_mov_b32_e32 v0, s9
	ds_read_b32 v2, v0
	v_readlane_b32 s9, v254, 57
	s_waitcnt lgkmcnt(0)
	v_cmp_ne_u32_e32 vcc, 0, v2
	v_mov_b32_e32 v0, s9
	ds_read_b32 v0, v0
	s_cbranch_vccnz .LBB0_1792
	s_mov_b32 s9, 1
	s_branch .LBB0_1780

; __device__ __forceinline__ unsigned xb_ld(unsigned* p)              { return __hip_atomic_load(p, __ATOMIC_RELAXED, __HIP_MEMORY_SCOPE_AGENT); }
; __device__ __forceinline__ unsigned xb_add(unsigned* p, unsigned v) { return __hip_atomic_fetch_add(p, v, __ATOMIC_RELAXED, __HIP_MEMORY_SCOPE_AGENT); }
; #define XB_SPIN(cond, bar) do { unsigned _sp = 0; while (cond) { __builtin_amdgcn_s_sleep(1); \
;     if ((++_sp & 255u) == 0u) { if (xb_ld(&(bar)[XB_TMO])) break; if (_sp > XB_SPIN_CAP) { atomicAdd(&(bar)[XB_TMO], 1u); break; } } } } while (0)
; __device__ __forceinline__ void xcd_barrier(const XcdBarrier& b) {
;     asm volatile("s_waitcnt vmcnt(0)" ::: "memory");
;     __syncthreads();
;     if (threadIdx.x == 0) {
;         unsigned* bar = b.bar;
;         __builtin_amdgcn_s_waitcnt(0);
;         unsigned nloc = b.st[0], nx = b.st[1];
;         if (nloc == 0u) { xcd_barrier_complete(bar, b.x, nloc, nx); b.st[0] = nloc; b.st[1] = nx; }
;         const unsigned old = xb_add(&bar[XB_XSUB(b.x)], 1u);
;         const unsigned gen = old / nloc;
;         if (old + 1u == (gen + 1u) * nloc) {
;             __builtin_amdgcn_fence(__ATOMIC_RELEASE, "agent");
;             asm volatile("s_waitcnt vmcnt(0)" ::: "memory");
;             const unsigned og = xb_add(&bar[XB_TOP], 1u);
;             const unsigned tg = og / nx;
;             if (og + 1u == (tg + 1u) * nx) xb_add(&bar[XB_TOPGEN], 1u);
;             else XB_SPIN(xb_ld(&bar[XB_TOPGEN]) == tg, bar);
;             __builtin_amdgcn_fence(__ATOMIC_ACQUIRE, "agent");
;             xb_add(&bar[XB_XGEN(b.x)], 1u);
;             asm volatile("s_waitcnt vmcnt(0)" ::: "memory");
;         } else {
;             XB_SPIN(xb_ld(&bar[XB_XGEN(b.x)]) == gen, bar);
;             __builtin_amdgcn_fence(__ATOMIC_ACQUIRE, "agent");
;             asm volatile("s_waitcnt vmcnt(0)" ::: "memory");
;         }
;     }
;     __syncthreads();
.LBB0_1868:
	s_add_i32 s0, s66, 3
	s_mov_b32 s86, s0
	s_cmp_ge_i32 s0, s27
	s_cbranch_scc1 .LBB0_1922
	s_waitcnt vmcnt(0)
	s_waitcnt vmcnt(0) lgkmcnt(0)
	s_barrier
	s_mov_b64 s[0:1], exec
	v_readlane_b32 s8, v252, 32
	v_readlane_b32 s9, v252, 33
	s_and_b64 s[8:9], s[0:1], s[8:9]
	s_mov_b64 exec, s[8:9]
	s_cbranch_execz .LBB0_1921
	s_cmp_eq_u32 s86, 20
	s_cbranch_scc1 .Lgb_orig_g4
	v_mov_b32_e32 v0, 0x23fc8
	ds_read_b32 v1, v0
	s_waitcnt lgkmcnt(0)
	v_readfirstlane_b32 s40, v1
	s_cmp_eq_u32 s40, 1
	s_cbranch_scc0 .Lgb_orig_g4
	s_and_b32 s40, s2, 7
	s_lshl_b32 s40, s40, 7
	s_add_u32 s38, s24, 0x313800
	s_addc_u32 s39, s25, 0
	v_mov_b32_e32 v0, s40
	v_mov_b32_e32 v1, 1
	global_atomic_add v2, v0, v1, s[38:39] sc0
	s_mov_b32 s40, 0
	s_waitcnt vmcnt(0)
	buffer_inv sc1
	v_or_b32_e32 v2, 31, v2
	v_add_u32_e32 v2, 1, v2
.Lgb_spin_g4:
	global_load_dword v3, v0, s[38:39] sc1
	s_waitcnt vmcnt(0)
	v_sub_u32_e32 v3, v3, v2
	v_cmp_gt_i32_e32 vcc, 0, v3
	s_cbranch_vccz .Lgb_done_g4
	s_sleep 1
	s_add_i32 s40, s40, 1
	s_cmp_lt_u32 s40, 0x100000
	s_cbranch_scc1 .Lgb_spin_g4
.Lgb_done_g4:
	s_branch .LBB0_1921
.Lgb_orig_g4:
	v_readlane_b32 s8, v254, 56
	s_waitcnt vmcnt(0) expcnt(0) lgkmcnt(0)
	s_nop 0
	v_mov_b32_e32 v0, s8
	ds_read_b32 v2, v0
	v_readlane_b32 s8, v254, 57
	s_waitcnt lgkmcnt(0)
	v_cmp_ne_u32_e32 vcc, 0, v2
	v_mov_b32_e32 v0, s8
	ds_read_b32 v0, v0
	s_cbranch_vccnz .LBB0_1885
	s_mov_b32 s8, 1
	s_branch .LBB0_1873
